# fused diff-attn: counted vmcnt waits account for the second V DMA piece (vmcnt 2->3, 1->2)
# speedup vs baseline: 1.0751x; 1.0003x over previous
; #define WAIT_BAR(N) asm volatile("s_waitcnt vmcnt(" #N ") lgkmcnt(0)\n\ts_barrier":::"memory")
;   #define DMA_K(t,slot) glds16(ksrc+(long)(t)*KVBLK*DM,(unsigned)__builtin_amdgcn_readfirstlane(kdst+(slot)))
;   #define DMA_V(t,slot) glds16(vsrc+(long)(t)*KVBLK*DM,(unsigned)__builtin_amdgcn_readfirstlane(vdst+(slot)))
;   #define CMASK(P0,P1,t) do{int jb_=(t)-(NT-4); if(jb_>=0)cmask(P0,P1,jb_,qrel,hi);}while(0)
;   #define START(P0,P1) do{ const float rm=rowmax(P0,P1); resc=false; \
;     { const float dl=rm; mhat=fadd_s(mhat,dl); \
;       _Pragma("unroll") for(int r=0;r<16;++r){P0[r]=fsub_s(P0[r],dl);P1[r]=fsub_s(P1[r],dl);} \
;       _Pragma("unroll") for(int r=0;r<16;++r)negm[r]=-mhat; asm volatile("":"+v"(negm)); } \
;     _Pragma("unroll") for(int r=0;r<16;++r)P0[r]=__builtin_amdgcn_exp2f(P0[r]); }while(0)
;   #define ROT() do{sl_prev=sl_cur;sl_cur=sl_next;sl_next=(sl_next==(NSLOT-1)*SLOTB)?0:sl_next+SLOTB;}while(0)
;   #define CMASK(P0,P1,t) do{}while(0)
;   #define CMASK(P0,P1,t) do{int jb_=(t)-(NT-4); if(jb_>=0)cmask(P0,P1,jb_,qrel,hi);}while(0)
; template<int THRL> __device__ __forceinline__ void attn_unit(int b,int colq,int colk,int colv,int colo,int qb,const bf16*Q,const bf16*__restrict__ K,const bf16*__restrict__ V,bf16*O,char*shm,const int tid_in){
;     ...
;   f32x16 pA0,pA1,pB0,pB1;
;   int sl_prev=0,sl_cur=0,sl_next=SLOTB;
;     ...
;   DMA_K(2,2*SLOTB);
;   WAIT_BAR(3);
;   qkt(pA0,pA1,Kbase,qr,negm,r32,hi);asm volatile("s_nop 15\n\ts_nop 7":"+v"(pA0),"+v"(pA1));CMASK(pA0,pA1,0);
;   START(pA0,pA1);
;   _Pragma("unroll") for(int r=0;r<16;++r)pA1[r]=__builtin_amdgcn_exp2f(pA1[r]);
;   WAIT_BAR(0);
;   DMA_K(3,0);DMA_V(1,SLOTB);
;   ROT();
;   kload8(kf,kp0+sl_cur);
;   WAIT_BAR(2);
.LBB0_240:
	v_lshlrev_b32_e32 v0, 1, v36
	v_and_b32_e32 v247, 32, v0
	v_lshlrev_b32_e32 v0, 4, v36
	v_and_b32_e32 v0, 0xc0, v0
	v_lshl_or_b32 v245, v243, 8, v0
	v_add_u32_e32 v0, 0, v247
	v_add3_u32 v254, v0, v244, v245
	v_max3_f32 v0, v18, v19, v2
	v_max3_f32 v36, v20, v21, v3
	s_and_b32 s15, s15, 0x3fffffc0
	v_max3_f32 v0, v0, v4, v5
	v_max3_f32 v36, v36, v24, v25
	s_add_i32 s17, s19, 0x100
	v_max3_f32 v0, v0, v22, v23
	v_max3_f32 v36, v36, v8, v9
	s_lshl_b32 s15, s15, 2
	v_max3_f32 v0, v0, v6, v7
	v_max3_f32 v36, v36, v28, v29
	s_add_i32 s37, s15, 0
	v_max3_f32 v0, v0, v26, v27
	v_max3_f32 v36, v36, v12, v13
	s_lshr_b32 s40, s17, 6
	v_max3_f32 v0, v0, v10, v11
	v_max3_f32 v36, v36, v32, v33
	s_cmp_lg_u32 0, -1
	v_max3_f32 v0, v0, v30, v31
	v_max3_f32 v36, v36, v16, v17
	v_lshl_add_u64 v[198:199], v[34:35], 0, s[96:97]
	v_max3_f32 v0, v0, v14, v15
	s_mov_b32 s16, 1
	v_max_f32_e32 v0, v0, v36
	s_mov_b32 s20, 0
	v_mov_b32_e32 v36, v0
	s_nop 1
	v_permlane32_swap_b32_e32 v0, v36
	v_max_f32_e32 v0, v0, v36
	v_lshlrev_b32_e32 v255, 4, v243
	v_add_f32_e32 v252, v1, v0
	v_sub_f32_e32 v2, v2, v0
	v_sub_f32_e32 v3, v3, v0
	v_sub_f32_e32 v18, v18, v0
	v_sub_f32_e32 v19, v19, v0
	v_sub_f32_e32 v20, v20, v0
	s_nop 0
	v_xor_b32_e32 v48, 0x80000000, v252
	v_mov_b32_e32 v49, v48
	v_mov_b32_e32 v50, v48
	v_mov_b32_e32 v51, v48
	v_mov_b32_e32 v52, v48
	v_mov_b32_e32 v53, v48
	v_mov_b32_e32 v54, v48
	v_mov_b32_e32 v55, v48
	v_mov_b32_e32 v56, v48
	v_mov_b32_e32 v57, v48
	v_mov_b32_e32 v58, v48
	v_mov_b32_e32 v59, v48
	v_mov_b32_e32 v60, v48
	v_mov_b32_e32 v61, v48
	v_mov_b32_e32 v62, v48
	v_mov_b32_e32 v63, v48
	s_waitcnt vmcnt(0) lgkmcnt(0)
	s_barrier
	v_exp_f32_e32 v64, v2
	v_exp_f32_e32 v65, v3
	v_lshl_add_u64 v[2:3], v[196:197], 0, s[60:61]
	s_mov_b32 s15, m0
	s_mov_b32 m0, s38
	s_nop 0
	global_load_lds_dwordx4 v[2:3], off
	s_mov_b32 m0, s15
	s_cselect_b32 s15, 0, 0
	s_add_i32 s14, s15, s14
	s_add_i32 s14, s14, 0x8000
	s_mov_b32 s15, m0
	s_mov_b32 m0, s14
	s_nop 0
	global_load_lds_dwordx4 v[198:199], off
	s_mov_b32 m0, s15
	s_add_i32 s46, s14, 0xe780
	s_mov_b32 s47, m0
	s_mov_b32 m0, s46
	s_nop 0
	global_load_lds_dwordx4 v[198:199], off offset:128
	s_mov_b32 m0, s47
	ds_read_b128 v[188:191], v253 offset:8192
	ds_read_b128 v[184:187], v253 offset:8704
	ds_read_b128 v[180:183], v253 offset:10240
	ds_read_b128 v[176:179], v253 offset:10752
	ds_read_b128 v[172:175], v253 offset:12288
	ds_read_b128 v[168:171], v253 offset:12800
	ds_read_b128 v[164:167], v253 offset:14336
	ds_read_b128 v[160:163], v253 offset:14848
	v_sub_f32_e32 v4, v4, v0
	v_sub_f32_e32 v21, v21, v0
	v_sub_f32_e32 v5, v5, v0
	v_sub_f32_e32 v22, v22, v0
	v_sub_f32_e32 v6, v6, v0
	v_sub_f32_e32 v23, v23, v0
	v_sub_f32_e32 v7, v7, v0
	v_sub_f32_e32 v24, v24, v0
	v_sub_f32_e32 v8, v8, v0
	v_sub_f32_e32 v25, v25, v0
	v_sub_f32_e32 v9, v9, v0
	v_sub_f32_e32 v26, v26, v0
	v_sub_f32_e32 v10, v10, v0
	v_sub_f32_e32 v27, v27, v0
	v_sub_f32_e32 v11, v11, v0
	v_sub_f32_e32 v28, v28, v0
	v_sub_f32_e32 v12, v12, v0
	v_sub_f32_e32 v29, v29, v0
	v_sub_f32_e32 v13, v13, v0
	v_sub_f32_e32 v30, v30, v0
	v_sub_f32_e32 v14, v14, v0
	v_sub_f32_e32 v31, v31, v0
	v_sub_f32_e32 v15, v15, v0
	v_sub_f32_e32 v32, v32, v0
	v_sub_f32_e32 v16, v16, v0
	v_sub_f32_e32 v33, v33, v0
	v_sub_f32_e32 v0, v17, v0
	v_exp_f32_e32 v80, v18
	v_exp_f32_e32 v81, v19
	v_exp_f32_e32 v82, v20
	v_exp_f32_e32 v83, v21
	v_exp_f32_e32 v84, v22
	v_exp_f32_e32 v85, v23
	v_exp_f32_e32 v86, v24
	v_exp_f32_e32 v87, v25
	v_exp_f32_e32 v88, v26
	v_exp_f32_e32 v89, v27
	v_exp_f32_e32 v90, v28
	v_exp_f32_e32 v91, v29
	v_exp_f32_e32 v92, v30
	v_exp_f32_e32 v93, v31
	v_exp_f32_e32 v94, v32
	v_exp_f32_e32 v95, v33
	v_exp_f32_e32 v66, v4
	v_exp_f32_e32 v67, v5
	v_exp_f32_e32 v68, v6
	v_exp_f32_e32 v69, v7
	v_exp_f32_e32 v70, v8
	v_exp_f32_e32 v71, v9
	v_exp_f32_e32 v72, v10
	v_exp_f32_e32 v73, v11
	v_exp_f32_e32 v74, v12
	v_exp_f32_e32 v75, v13
	v_exp_f32_e32 v76, v14
	v_exp_f32_e32 v77, v15
	v_exp_f32_e32 v78, v16
	v_exp_f32_e32 v79, v0
	s_waitcnt vmcnt(3) lgkmcnt(0)
	s_barrier
	s_andn2_b64 vcc, exec, s[2:3]
	v_cmp_gt_u32_e64 s[2:3], 32, v206
	v_lshl_add_u32 v250, v242, 2, s37
	s_cbranch_vccnz .LBB0_256
	v_mov_b32_e32 v14, v1
	v_mov_b32_e32 v15, v1
	v_lshl_add_u64 v[200:201], v[34:35], 0, s[60:61]
	s_mov_b64 s[14:15], 0x230000
	v_mov_b32_e32 v0, v1
	v_mov_b32_e32 v2, v1
	v_mov_b32_e32 v3, v1
	v_mov_b32_e32 v4, v1
	v_mov_b32_e32 v5, v1
	v_mov_b32_e32 v6, v1
	v_mov_b32_e32 v7, v1
	v_mov_b32_e32 v8, v1
	v_mov_b32_e32 v9, v1
	v_mov_b32_e32 v10, v1
	v_mov_b32_e32 v11, v1
	v_mov_b32_e32 v12, v1
	v_mov_b32_e32 v13, v1
	v_mov_b64_e32 v[46:47], v[14:15]
	v_mov_b64_e32 v[30:31], v[14:15]
	v_lshl_add_u64 v[202:203], v[196:197], 0, s[14:15]
	s_mov_b32 s14, 0
	s_movk_i32 s20, 0x4000
	s_movk_i32 s22, 0x2000
	v_mov_b32_e32 v224, 0
	s_mov_b32 s21, 6
	v_mov_b64_e32 v[44:45], v[12:13]
	v_mov_b64_e32 v[42:43], v[10:11]
	v_mov_b64_e32 v[40:41], v[8:9]
	v_mov_b64_e32 v[38:39], v[6:7]
	v_mov_b64_e32 v[36:37], v[4:5]
	v_mov_b64_e32 v[34:35], v[2:3]
	v_mov_b64_e32 v[32:33], v[0:1]
	v_mov_b64_e32 v[28:29], v[12:13]
	v_mov_b64_e32 v[26:27], v[10:11]
	v_mov_b64_e32 v[24:25], v[8:9]
	v_mov_b64_e32 v[22:23], v[6:7]
	v_mov_b64_e32 v[20:21], v[4:5]
	v_mov_b64_e32 v[18:19], v[2:3]
	v_mov_b64_e32 v[16:17], v[0:1]

; #define WAIT_BAR(N) asm volatile("s_waitcnt vmcnt(" #N ") lgkmcnt(0)\n\ts_barrier":::"memory")
;   #define RESC() do{ if(resc){ asm volatile("s_waitcnt lgkmcnt(0)":::"memory"); \
;       _Pragma("unroll") for(int d_=0;d_<2;++d_) _Pragma("unroll") for(int r=0;r<16;++r)o[d_][r]*=wsf[crow(r,hi)]; } }while(0)
;   #define ROT() do{sl_prev=sl_cur;sl_cur=sl_next;sl_next=(sl_next==(NSLOT-1)*SLOTB)?0:sl_next+SLOTB;}while(0)
; template<int THRL> __device__ __forceinline__ void attn_unit(int b,int colq,int colk,int colv,int colo,int qb,const bf16*Q,const bf16*__restrict__ K,const bf16*__restrict__ V,bf16*O,char*shm,const int tid_in){
;     ...
;   int t=1;
;     ...
;   for(;t+5<NT;t+=2){
;     STEP(pB0,pB1,pA0,pA1,t,true,true,true);     WAIT_BAR(2); RESC(); ROT();
.LBB0_243:
	v_add_u32_e32 v0, s45, v254
	s_waitcnt lgkmcnt(14)
	v_mfma_f32_32x32x16_bf16 v[32:47], v[156:159], v[192:195], v[32:47]
	v_exp_f32_e32 v112, v112
	v_exp_f32_e32 v113, v113
	ds_read_b64_tr_b16 v[192:193], v0 offset:24576
	ds_read_b64_tr_b16 v[194:195], v0 offset:25088
	s_waitcnt lgkmcnt(14)
	v_mfma_f32_32x32x16_bf16 v[16:31], v[156:159], v[80:83], v[16:31]
	v_exp_f32_e32 v114, v114
	v_exp_f32_e32 v115, v115
	ds_read_b64_tr_b16 v[80:81], v0 offset:28672
	ds_read_b64_tr_b16 v[82:83], v0 offset:29184
	s_waitcnt lgkmcnt(14)
	v_mfma_f32_32x32x16_bf16 v[32:47], v[152:155], v[2:5], v[32:47]
	v_exp_f32_e32 v116, v116
	v_exp_f32_e32 v117, v117
	ds_read_b64_tr_b16 v[2:3], v0 offset:25600
	ds_read_b64_tr_b16 v[4:5], v0 offset:26112
	s_waitcnt lgkmcnt(14)
	v_mfma_f32_32x32x16_bf16 v[16:31], v[152:155], v[6:9], v[16:31]
	v_exp_f32_e32 v118, v118
	v_exp_f32_e32 v119, v119
	ds_read_b64_tr_b16 v[6:7], v0 offset:29696
	ds_read_b64_tr_b16 v[8:9], v0 offset:30208
	s_waitcnt lgkmcnt(14)
	v_mfma_f32_32x32x16_bf16 v[32:47], v[144:147], v[10:13], v[32:47]
	v_exp_f32_e32 v120, v120
	v_exp_f32_e32 v121, v121
	ds_read_b64_tr_b16 v[10:11], v0 offset:26624
	ds_read_b64_tr_b16 v[12:13], v0 offset:27136
	s_waitcnt lgkmcnt(14)
	v_mfma_f32_32x32x16_bf16 v[16:31], v[144:147], v[64:67], v[16:31]
	v_exp_f32_e32 v122, v122
	v_exp_f32_e32 v123, v123
	ds_read_b64_tr_b16 v[64:65], v0 offset:30720
	ds_read_b64_tr_b16 v[66:67], v0 offset:31232
	s_waitcnt lgkmcnt(14)
	v_mfma_f32_32x32x16_bf16 v[32:47], v[136:139], v[68:71], v[32:47]
	v_exp_f32_e32 v124, v124
	v_exp_f32_e32 v125, v125
	ds_read_b64_tr_b16 v[68:69], v0 offset:27648
	ds_read_b64_tr_b16 v[70:71], v0 offset:28160
	s_waitcnt lgkmcnt(14)
	v_mfma_f32_32x32x16_bf16 v[16:31], v[136:139], v[72:75], v[16:31]
	v_exp_f32_e32 v126, v126
	v_exp_f32_e32 v127, v127
	ds_read_b64_tr_b16 v[72:73], v0 offset:31744
	ds_read_b64_tr_b16 v[74:75], v0 offset:32256
	s_waitcnt lgkmcnt(14)
	v_mfma_f32_32x32x16_bf16 v[226:241], v[156:159], v[192:195], v[226:241]
	v_exp_f32_e32 v96, v96
	v_exp_f32_e32 v97, v97
	s_waitcnt lgkmcnt(12)
	v_mfma_f32_32x32x16_bf16 v[208:223], v[156:159], v[80:83], v[208:223]
	v_exp_f32_e32 v98, v98
	v_exp_f32_e32 v99, v99
	v_add_u32_e32 v0, s20, v253
	ds_read_b128 v[76:79], v0
	ds_read_b128 v[184:187], v0 offset:512
	s_waitcnt lgkmcnt(12)
	v_mfma_f32_32x32x16_bf16 v[226:241], v[152:155], v[2:5], v[226:241]
	v_exp_f32_e32 v100, v100
	v_exp_f32_e32 v101, v101
	ds_read_b128 v[188:191], v0 offset:2048
	ds_read_b128 v[180:183], v0 offset:2560
	s_waitcnt lgkmcnt(12)
	v_mfma_f32_32x32x16_bf16 v[208:223], v[152:155], v[6:9], v[208:223]
	v_exp_f32_e32 v102, v102
	v_exp_f32_e32 v103, v103
	ds_read_b128 v[176:179], v0 offset:4096
	ds_read_b128 v[172:175], v0 offset:4608
	s_waitcnt lgkmcnt(12)
	v_mfma_f32_32x32x16_bf16 v[226:241], v[144:147], v[10:13], v[226:241]
	v_exp_f32_e32 v104, v104
	v_exp_f32_e32 v105, v105
	ds_read_b128 v[168:171], v0 offset:6144
	ds_read_b128 v[164:167], v0 offset:6656
	s_waitcnt lgkmcnt(12)
	v_mfma_f32_32x32x16_bf16 v[208:223], v[144:147], v[64:67], v[208:223]
	v_exp_f32_e32 v106, v106
	v_exp_f32_e32 v107, v107
	s_waitcnt lgkmcnt(10)
	v_mfma_f32_32x32x16_bf16 v[226:241], v[136:139], v[68:71], v[226:241]
	v_exp_f32_e32 v108, v108
	v_exp_f32_e32 v109, v109
	s_waitcnt lgkmcnt(8)
	v_mfma_f32_32x32x16_bf16 v[208:223], v[136:139], v[72:75], v[208:223]
	v_exp_f32_e32 v110, v110
	v_exp_f32_e32 v111, v111
	s_waitcnt vmcnt(3) lgkmcnt(0)
	s_barrier
	s_andn2_b64 vcc, exec, s[14:15]
	v_add_u32_e32 v0, s37, v255
	s_cbranch_vccnz .LBB0_245
	s_waitcnt lgkmcnt(0)
	ds_read_b128 v[2:5], v0 offset:49248
	ds_read_b128 v[6:9], v0 offset:49216
	ds_read_b128 v[10:13], v0 offset:49184
	ds_read_b128 v[64:67], v0 offset:49152
	s_waitcnt lgkmcnt(3)
	v_pk_mul_f32 v[44:45], v[44:45], v[2:3]
	s_waitcnt lgkmcnt(2)
	v_pk_mul_f32 v[40:41], v[40:41], v[6:7]
	s_waitcnt lgkmcnt(1)
	v_pk_mul_f32 v[36:37], v[36:37], v[10:11]
	v_pk_mul_f32 v[46:47], v[46:47], v[4:5]
	v_pk_mul_f32 v[42:43], v[42:43], v[8:9]
	v_pk_mul_f32 v[38:39], v[38:39], v[12:13]
	s_waitcnt lgkmcnt(0)
	v_pk_mul_f32 v[34:35], v[34:35], v[66:67]
	v_pk_mul_f32 v[32:33], v[32:33], v[64:65]
	v_pk_mul_f32 v[28:29], v[28:29], v[2:3]
	v_pk_mul_f32 v[24:25], v[24:25], v[6:7]
	v_pk_mul_f32 v[20:21], v[20:21], v[10:11]
	v_pk_mul_f32 v[30:31], v[30:31], v[4:5]
	v_pk_mul_f32 v[26:27], v[26:27], v[8:9]
	v_pk_mul_f32 v[22:23], v[22:23], v[12:13]
	v_pk_mul_f32 v[18:19], v[18:19], v[66:67]
	v_pk_mul_f32 v[16:17], v[16:17], v[64:65]
	v_pk_mul_f32 v[238:239], v[238:239], v[2:3]
	v_pk_mul_f32 v[234:235], v[234:235], v[6:7]
	v_pk_mul_f32 v[230:231], v[230:231], v[10:11]
	v_pk_mul_f32 v[240:241], v[240:241], v[4:5]
	v_pk_mul_f32 v[236:237], v[236:237], v[8:9]
	v_pk_mul_f32 v[232:233], v[232:233], v[12:13]
	v_pk_mul_f32 v[228:229], v[228:229], v[66:67]
	v_pk_mul_f32 v[226:227], v[226:227], v[64:65]
	v_pk_mul_f32 v[220:221], v[220:221], v[2:3]
	v_pk_mul_f32 v[216:217], v[216:217], v[6:7]
	v_pk_mul_f32 v[212:213], v[212:213], v[10:11]
	v_pk_mul_f32 v[222:223], v[222:223], v[4:5]
	v_pk_mul_f32 v[218:219], v[218:219], v[8:9]
	v_pk_mul_f32 v[214:215], v[214:215], v[12:13]
	v_pk_mul_f32 v[210:211], v[210:211], v[66:67]
	v_pk_mul_f32 v[208:209], v[208:209], v[64:65]

; #define WAIT_BAR(N) asm volatile("s_waitcnt vmcnt(" #N ") lgkmcnt(0)\n\ts_barrier":::"memory")
;   #define RESC() do{ if(resc){ asm volatile("s_waitcnt lgkmcnt(0)":::"memory"); \
;       _Pragma("unroll") for(int d_=0;d_<2;++d_) _Pragma("unroll") for(int r=0;r<16;++r)o[d_][r]*=wsf[crow(r,hi)]; } }while(0)
;   #define ROT() do{sl_prev=sl_cur;sl_cur=sl_next;sl_next=(sl_next==(NSLOT-1)*SLOTB)?0:sl_next+SLOTB;}while(0)
; template<int THRL> __device__ __forceinline__ void attn_unit(int b,int colq,int colk,int colv,int colo,int qb,const bf16*Q,const bf16*__restrict__ K,const bf16*__restrict__ V,bf16*O,char*shm,const int tid_in){
;     ...
;   int t=1;
;     ...
;   for(;t+5<NT;t+=2){
;     STEP(pB0,pB1,pA0,pA1,t,true,true,true);     WAIT_BAR(2); RESC(); ROT();
;     STEP(pA0,pA1,pB0,pB1,t+1,true,true,true);   WAIT_BAR(2); RESC(); ROT();
.LBB0_246:
	v_add_u32_e32 v14, s45, v254
	s_waitcnt lgkmcnt(14)
	v_mfma_f32_32x32x16_bf16 v[32:47], v[156:159], v[160:163], v[32:47]
	v_exp_f32_e32 v80, v80
	v_exp_f32_e32 v81, v81
	ds_read_b64_tr_b16 v[160:161], v14 offset:24576
	ds_read_b64_tr_b16 v[162:163], v14 offset:25088
	s_waitcnt lgkmcnt(14)
	v_mfma_f32_32x32x16_bf16 v[16:31], v[156:159], v[112:115], v[16:31]
	v_exp_f32_e32 v82, v82
	v_exp_f32_e32 v83, v83
	ds_read_b64_tr_b16 v[112:113], v14 offset:28672
	ds_read_b64_tr_b16 v[114:115], v14 offset:29184
	s_waitcnt lgkmcnt(14)
	v_mfma_f32_32x32x16_bf16 v[32:47], v[152:155], v[2:5], v[32:47]
	v_exp_f32_e32 v84, v84
	v_exp_f32_e32 v85, v85
	ds_read_b64_tr_b16 v[2:3], v14 offset:25600
	ds_read_b64_tr_b16 v[4:5], v14 offset:26112
	s_waitcnt lgkmcnt(14)
	v_mfma_f32_32x32x16_bf16 v[16:31], v[152:155], v[6:9], v[16:31]
	v_exp_f32_e32 v86, v86
	v_exp_f32_e32 v87, v87
	ds_read_b64_tr_b16 v[6:7], v14 offset:29696
	ds_read_b64_tr_b16 v[8:9], v14 offset:30208
	s_waitcnt lgkmcnt(14)
	v_mfma_f32_32x32x16_bf16 v[32:47], v[144:147], v[10:13], v[32:47]
	v_exp_f32_e32 v88, v88
	v_exp_f32_e32 v89, v89
	ds_read_b64_tr_b16 v[10:11], v14 offset:26624
	ds_read_b64_tr_b16 v[12:13], v14 offset:27136
	s_waitcnt lgkmcnt(14)
	v_mfma_f32_32x32x16_bf16 v[16:31], v[144:147], v[96:99], v[16:31]
	v_exp_f32_e32 v90, v90
	v_exp_f32_e32 v91, v91
	ds_read_b64_tr_b16 v[96:97], v14 offset:30720
	ds_read_b64_tr_b16 v[98:99], v14 offset:31232
	s_waitcnt lgkmcnt(14)
	v_mfma_f32_32x32x16_bf16 v[32:47], v[136:139], v[100:103], v[32:47]
	v_exp_f32_e32 v92, v92
	v_exp_f32_e32 v93, v93
	ds_read_b64_tr_b16 v[100:101], v14 offset:27648
	ds_read_b64_tr_b16 v[102:103], v14 offset:28160
	s_waitcnt lgkmcnt(14)
	v_mfma_f32_32x32x16_bf16 v[16:31], v[136:139], v[104:107], v[16:31]
	v_exp_f32_e32 v94, v94
	v_exp_f32_e32 v95, v95
	ds_read_b64_tr_b16 v[104:105], v14 offset:31744
	ds_read_b64_tr_b16 v[106:107], v14 offset:32256
	s_waitcnt lgkmcnt(14)
	v_mfma_f32_32x32x16_bf16 v[226:241], v[156:159], v[160:163], v[226:241]
	v_exp_f32_e32 v64, v64
	v_exp_f32_e32 v65, v65
	s_waitcnt lgkmcnt(12)
	v_mfma_f32_32x32x16_bf16 v[208:223], v[156:159], v[112:115], v[208:223]
	v_exp_f32_e32 v66, v66
	v_exp_f32_e32 v67, v67
	v_add_u32_e32 v14, s41, v253
	ds_read_b128 v[188:191], v14
	ds_read_b128 v[184:187], v14 offset:512
	s_waitcnt lgkmcnt(12)
	v_mfma_f32_32x32x16_bf16 v[226:241], v[152:155], v[2:5], v[226:241]
	v_exp_f32_e32 v68, v68
	v_exp_f32_e32 v69, v69
	ds_read_b128 v[180:183], v14 offset:2048
	ds_read_b128 v[176:179], v14 offset:2560
	s_waitcnt lgkmcnt(12)
	v_mfma_f32_32x32x16_bf16 v[208:223], v[152:155], v[6:9], v[208:223]
	v_exp_f32_e32 v70, v70
	v_exp_f32_e32 v71, v71
	ds_read_b128 v[172:175], v14 offset:4096
	ds_read_b128 v[168:171], v14 offset:4608
	s_waitcnt lgkmcnt(12)
	v_mfma_f32_32x32x16_bf16 v[226:241], v[144:147], v[10:13], v[226:241]
	v_exp_f32_e32 v72, v72
	v_exp_f32_e32 v73, v73
	ds_read_b128 v[164:167], v14 offset:6144
	ds_read_b128 v[160:163], v14 offset:6656
	s_waitcnt lgkmcnt(12)
	v_mfma_f32_32x32x16_bf16 v[208:223], v[144:147], v[96:99], v[208:223]
	v_exp_f32_e32 v74, v74
	v_exp_f32_e32 v75, v75
	s_waitcnt lgkmcnt(10)
	v_mfma_f32_32x32x16_bf16 v[226:241], v[136:139], v[100:103], v[226:241]
	v_exp_f32_e32 v76, v76
	v_exp_f32_e32 v77, v77
	s_waitcnt lgkmcnt(8)
	v_mfma_f32_32x32x16_bf16 v[208:223], v[136:139], v[104:107], v[208:223]
	v_exp_f32_e32 v78, v78
	v_exp_f32_e32 v79, v79
	s_waitcnt vmcnt(3) lgkmcnt(0)
	s_barrier
	s_andn2_b64 vcc, exec, s[14:15]
	s_cbranch_vccnz .LBB0_248
	s_waitcnt lgkmcnt(0)
	ds_read_b128 v[2:5], v0 offset:49248
	ds_read_b128 v[6:9], v0 offset:49216
	ds_read_b128 v[10:13], v0 offset:49184
	ds_read_b128 v[96:99], v0 offset:49152
	s_waitcnt lgkmcnt(3)
	v_pk_mul_f32 v[44:45], v[44:45], v[2:3]
	s_waitcnt lgkmcnt(2)
	v_pk_mul_f32 v[40:41], v[40:41], v[6:7]
	s_waitcnt lgkmcnt(1)
	v_pk_mul_f32 v[36:37], v[36:37], v[10:11]
	v_pk_mul_f32 v[46:47], v[46:47], v[4:5]
	v_pk_mul_f32 v[42:43], v[42:43], v[8:9]
	v_pk_mul_f32 v[38:39], v[38:39], v[12:13]
	s_waitcnt lgkmcnt(0)
	v_pk_mul_f32 v[34:35], v[34:35], v[98:99]
	v_pk_mul_f32 v[32:33], v[32:33], v[96:97]
	v_pk_mul_f32 v[28:29], v[28:29], v[2:3]
	v_pk_mul_f32 v[24:25], v[24:25], v[6:7]
	v_pk_mul_f32 v[20:21], v[20:21], v[10:11]
	v_pk_mul_f32 v[30:31], v[30:31], v[4:5]
	v_pk_mul_f32 v[26:27], v[26:27], v[8:9]
	v_pk_mul_f32 v[22:23], v[22:23], v[12:13]
	v_pk_mul_f32 v[18:19], v[18:19], v[98:99]
	v_pk_mul_f32 v[16:17], v[16:17], v[96:97]
	v_pk_mul_f32 v[238:239], v[238:239], v[2:3]
	v_pk_mul_f32 v[234:235], v[234:235], v[6:7]
	v_pk_mul_f32 v[230:231], v[230:231], v[10:11]
	v_pk_mul_f32 v[240:241], v[240:241], v[4:5]
	v_pk_mul_f32 v[236:237], v[236:237], v[8:9]
	v_pk_mul_f32 v[232:233], v[232:233], v[12:13]
	v_pk_mul_f32 v[228:229], v[228:229], v[98:99]
	v_pk_mul_f32 v[226:227], v[226:227], v[96:97]
	v_pk_mul_f32 v[220:221], v[220:221], v[2:3]
	v_pk_mul_f32 v[216:217], v[216:217], v[6:7]
	v_pk_mul_f32 v[212:213], v[212:213], v[10:11]
	v_pk_mul_f32 v[222:223], v[222:223], v[4:5]
	v_pk_mul_f32 v[218:219], v[218:219], v[8:9]
	v_pk_mul_f32 v[214:215], v[214:215], v[12:13]
	v_pk_mul_f32 v[210:211], v[210:211], v[98:99]
	v_pk_mul_f32 v[208:209], v[208:209], v[96:97]

;   #define RESC() do{ if(resc){ asm volatile("s_waitcnt lgkmcnt(0)":::"memory"); \
;       _Pragma("unroll") for(int d_=0;d_<2;++d_) _Pragma("unroll") for(int r=0;r<16;++r)o[d_][r]*=wsf[crow(r,hi)]; } }while(0)
;   #define ROT() do{sl_prev=sl_cur;sl_cur=sl_next;sl_next=(sl_next==(NSLOT-1)*SLOTB)?0:sl_next+SLOTB;}while(0)
;   #define ENDW(tt) do{ if((tt)+3<NT){WAIT_BAR(2);} else if((tt)+2<NT){WAIT_BAR(1);} else {WAIT_BAR(0);} }while(0)
; template<int THRL> __device__ __forceinline__ void attn_unit(int b,int colq,int colk,int colv,int colo,int qb,const bf16*Q,const bf16*__restrict__ K,const bf16*__restrict__ V,bf16*O,char*shm,const int tid_in){
;     ...
;   for(;t+1<NT;t+=2){
;     STEP(pB0,pB1,pA0,pA1,t,(t+3<NT),(t+1<NT),(t+1<NT));       ENDW(t);   RESC(); ROT();
;     STEP(pA0,pA1,pB0,pB1,t+1,(t+4<NT),(t+2<NT),(t+2<NT));     ENDW(t+1); RESC(); ROT();
.LBB0_297:
	s_andn2_b64 vcc, exec, s[18:19]
	s_cbranch_vccnz .LBB0_299
	s_waitcnt vmcnt(2) lgkmcnt(0)
	s_barrier

;   #define RESC() do{ if(resc){ asm volatile("s_waitcnt lgkmcnt(0)":::"memory"); \
;       _Pragma("unroll") for(int d_=0;d_<2;++d_) _Pragma("unroll") for(int r=0;r<16;++r)o[d_][r]*=wsf[crow(r,hi)]; } }while(0)
;   #define ROT() do{sl_prev=sl_cur;sl_cur=sl_next;sl_next=(sl_next==(NSLOT-1)*SLOTB)?0:sl_next+SLOTB;}while(0)
;   #define ENDW(tt) do{ if((tt)+3<NT){WAIT_BAR(2);} else if((tt)+2<NT){WAIT_BAR(1);} else {WAIT_BAR(0);} }while(0)
; template<int THRL> __device__ __forceinline__ void attn_unit(int b,int colq,int colk,int colv,int colo,int qb,const bf16*Q,const bf16*__restrict__ K,const bf16*__restrict__ V,bf16*O,char*shm,const int tid_in){
;     ...
;   for(;t+1<NT;t+=2){
;     STEP(pB0,pB1,pA0,pA1,t,(t+3<NT),(t+1<NT),(t+1<NT));       ENDW(t);   RESC(); ROT();
;     STEP(pA0,pA1,pB0,pB1,t+1,(t+4<NT),(t+2<NT),(t+2<NT));     ENDW(t+1); RESC(); ROT();
.LBB0_300:
	s_waitcnt vmcnt(3) lgkmcnt(0)
	s_barrier
	s_andn2_b64 vcc, exec, s[4:5]
	v_add_u32_e32 v225, s37, v255
	s_cbranch_vccz .LBB0_273
	s_branch .LBB0_274

;   #define RESC() do{ if(resc){ asm volatile("s_waitcnt lgkmcnt(0)":::"memory"); \
;       _Pragma("unroll") for(int d_=0;d_<2;++d_) _Pragma("unroll") for(int r=0;r<16;++r)o[d_][r]*=wsf[crow(r,hi)]; } }while(0)
;   #define ROT() do{sl_prev=sl_cur;sl_cur=sl_next;sl_next=(sl_next==(NSLOT-1)*SLOTB)?0:sl_next+SLOTB;}while(0)
;   #define ENDW(tt) do{ if((tt)+3<NT){WAIT_BAR(2);} else if((tt)+2<NT){WAIT_BAR(1);} else {WAIT_BAR(0);} }while(0)
; template<int THRL> __device__ __forceinline__ void attn_unit(int b,int colq,int colk,int colv,int colo,int qb,const bf16*Q,const bf16*__restrict__ K,const bf16*__restrict__ V,bf16*O,char*shm,const int tid_in){
;     ...
;   for(;t+1<NT;t+=2){
;     STEP(pB0,pB1,pA0,pA1,t,(t+3<NT),(t+1<NT),(t+1<NT));       ENDW(t);   RESC(); ROT();
;     STEP(pA0,pA1,pB0,pB1,t+1,(t+4<NT),(t+2<NT),(t+2<NT));     ENDW(t+1); RESC(); ROT();
.LBB0_303:
	s_andn2_b64 vcc, exec, s[4:5]
	s_cbranch_vccnz .LBB0_305
	s_waitcnt vmcnt(2) lgkmcnt(0)
	s_barrier

;   #define RESC() do{ if(resc){ asm volatile("s_waitcnt lgkmcnt(0)":::"memory"); \
;       _Pragma("unroll") for(int d_=0;d_<2;++d_) _Pragma("unroll") for(int r=0;r<16;++r)o[d_][r]*=wsf[crow(r,hi)]; } }while(0)
;   #define ROT() do{sl_prev=sl_cur;sl_cur=sl_next;sl_next=(sl_next==(NSLOT-1)*SLOTB)?0:sl_next+SLOTB;}while(0)
;   #define ENDW(tt) do{ if((tt)+3<NT){WAIT_BAR(2);} else if((tt)+2<NT){WAIT_BAR(1);} else {WAIT_BAR(0);} }while(0)
; template<int THRL> __device__ __forceinline__ void attn_unit(int b,int colq,int colk,int colv,int colo,int qb,const bf16*Q,const bf16*__restrict__ K,const bf16*__restrict__ V,bf16*O,char*shm,const int tid_in){
;     ...
;   for(;t+1<NT;t+=2){
;     STEP(pB0,pB1,pA0,pA1,t,(t+3<NT),(t+1<NT),(t+1<NT));       ENDW(t);   RESC(); ROT();
;     STEP(pA0,pA1,pB0,pB1,t+1,(t+4<NT),(t+2<NT),(t+2<NT));     ENDW(t+1); RESC(); ROT();
.LBB0_306:
	s_waitcnt vmcnt(3) lgkmcnt(0)
	s_barrier
	s_andn2_b64 vcc, exec, s[20:21]
	s_cbranch_vccz .LBB0_292
	s_branch .LBB0_293
